# PEER: gather waves at priority 1 during the token loop so the co-resident selecting wave yields (placement preserved)
# speedup vs baseline: 1.0013x; 1.0013x over previous
.LBB0_728:
	s_add_i32 s52, s12, s80
	s_cmpk_lt_i32 s52, 0x300
	s_cselect_b64 s[10:11], -1, 0
	s_cmpk_gt_i32 s52, 0x2ff
	s_cselect_b64 s[26:27], -1, 0
	s_and_b64 s[28:29], s[6:7], s[10:11]
	s_lshl_b32 s53, s49, 14
	s_xor_b64 s[28:29], s[28:29], -1
	s_and_saveexec_b64 s[30:31], s[28:29]
	s_xor_b64 s[28:29], exec, s[30:31]
	s_cbranch_execz .LBB0_803
	s_and_saveexec_b64 s[30:31], s[8:9]
	s_cbranch_execz .LBB0_802
	s_and_b64 s[10:11], s[10:11], exec
	s_cselect_b32 s61, 4, 8
	s_cselect_b32 s101, 11, 15
	s_add_i32 s62, s53, 0
	s_lshl_b32 s63, s12, 4
	s_mov_b64 s[34:35], 0
	v_mov_b32_e32 v223, v215
	s_setprio 1
	s_nop 0
	s_branch .LBB0_732

.Lpeer_normal_exit:
	s_setprio 0
	s_nop 0
	s_or_b64 exec, exec, s[30:31]
